# attention epilogues: og output stores marked nt
# baseline (speedup 1.0000x reference)
; DI unsigned pk2(float a, float b) { f32x2 v = {a, b}; bf16v2 r = __builtin_convertvector(v, bf16v2); return __builtin_bit_cast(unsigned, r); }
; DI float bf_lo(unsigned u) { return __uint_as_float(u << 16); }
; DI float bf_hi(unsigned u) { return __uint_as_float(u & 0xffff0000u); }
; DI size_t zrowU(int row0, int NT) { return ((size_t)((row0 >> 8) * NT) << 16) + (size_t)((((row0 >> 7) & 1) << 15) | (((row0 >> 5) & 1) << 14) | (((row0 >> 6) & 1) << 11)); }
; DI unsigned zlaneRC(int r5, int col) { return (unsigned)(((col >> 8) << 16) | ((r5 >> 4) << 13) | (((col >> 7) & 1) << 12) | (((col >> 5) & 3) << 9) | (((col >> 3) & 3) << 7) | ((r5 & 15) << 3) | (col & 7)); }
; DI float silu_mul(float o, float g) { return o * g * __builtin_amdgcn_rcpf(1.0f + __builtin_amdgcn_exp2f(g * -1.4426950408889634f)); }
; DI void attnB_item(bf16_t* z, int hh, int qs, LAS bf16_t* vs, int lane) {
;     ...
;     if (!metaq || c < NMETA) {
;         bf16_t* orow = z + zrowU(qrow0, 32) + zlaneRC(c, hh * 128 + 4 * h);
;         const bf16_t* grow = z + zrowU(qrow0, 32) + zlaneRC(c, 6144 + hh * 128 + 4 * h);
; #pragma unroll
;         for (int dt = 0; dt < 4; ++dt)
; #pragma unroll
;             for (int g = 0; g < 4; ++g) {
;                 const int d0 = (dt << 9) | (g << 7);
;                 const u32x2 gv = *(const u32x2*)(grow + d0);
;                 u32x2 o; o.x = pk2(silu_mul(acc[dt][4 * g], bf_lo(gv.x)), silu_mul(acc[dt][4 * g + 1], bf_hi(gv.x)));
;                 o.y = pk2(silu_mul(acc[dt][4 * g + 2], bf_lo(gv.y)), silu_mul(acc[dt][4 * g + 3], bf_hi(gv.y)));
;                 *(u32x2*)(orow + d0) = o;
;             }
.LBB0_157:
	v_cmp_gt_u32_e32 vcc, 16, v178
	s_or_b64 s[0:1], s[0:1], vcc
	s_and_saveexec_b64 s[4:5], s[0:1]
	s_xor_b64 s[0:1], exec, s[4:5]
	s_cbranch_execz .LBB0_130
	v_add_u32_e32 v0, s27, v183
	v_lshlrev_b32_e32 v66, 8, v0
	v_lshlrev_b32_e32 v0, 5, v0
	v_lshlrev_b32_e32 v67, 6, v180
	v_and_b32_e32 v0, 0x1000, v0
	v_and_b32_e32 v68, 0x780, v67
	v_and_b32_e32 v69, 4, v183
	v_or_b32_e32 v67, v68, v69
	v_and_or_b32 v70, v66, s12, v0
	v_or3_b32 v0, v67, v181, v70
	v_lshl_add_u64 v[146:147], v[0:1], 1, s[46:47]
	v_or3_b32 v0, v70, v69, v68
	s_mov_b32 s4, 0x180000
	v_add3_u32 v0, v0, v181, s4
	v_lshl_add_u64 v[148:149], v[0:1], 1, s[46:47]
	global_load_dwordx2 v[192:193], v[148:149], off
	global_load_dwordx2 v[194:195], v[148:149], off offset:256
	global_load_dwordx2 v[196:197], v[148:149], off offset:512
	global_load_dwordx2 v[198:199], v[148:149], off offset:768
	global_load_dwordx2 v[200:201], v[148:149], off offset:1024
	global_load_dwordx2 v[202:203], v[148:149], off offset:1280
	global_load_dwordx2 v[204:205], v[148:149], off offset:1536
	global_load_dwordx2 v[206:207], v[148:149], off offset:1792
	global_load_dwordx2 v[208:209], v[148:149], off offset:2048
	global_load_dwordx2 v[210:211], v[148:149], off offset:2304
	global_load_dwordx2 v[212:213], v[148:149], off offset:2560
	global_load_dwordx2 v[214:215], v[148:149], off offset:2816
	global_load_dwordx2 v[216:217], v[148:149], off offset:3072
	global_load_dwordx2 v[218:219], v[148:149], off offset:3328
	global_load_dwordx2 v[220:221], v[148:149], off offset:3584
	global_load_dwordx2 v[222:223], v[148:149], off offset:3840
	s_add_i32 s5, s26, s33
	s_and_b32 s5, s5, 7
	s_lshl_b32 s5, s5, 8
	s_mov_b64 vcc, exec
	s_mov_b64 exec, 1
	v_mov_b32_e32 v66, s5
	v_mov_b32_e32 v67, 1
	global_atomic_add v240, v66, v67, s[34:35] sc0
	s_mov_b64 exec, vcc
	s_mov_b32 s100, 1
	s_waitcnt vmcnt(16)
	v_lshlrev_b32_e32 v66, 16, v192
	v_and_b32_e32 v67, 0xffff0000, v192
	v_lshlrev_b32_e32 v68, 16, v193
	v_and_b32_e32 v69, 0xffff0000, v193
	v_mul_f32_e32 v70, 0xbfb8aa3b, v66
	v_mul_f32_e32 v71, 0xbfb8aa3b, v67
	v_mul_f32_e32 v72, 0xbfb8aa3b, v68
	v_mul_f32_e32 v73, 0xbfb8aa3b, v69
	v_exp_f32_e32 v70, v70
	v_exp_f32_e32 v71, v71
	v_exp_f32_e32 v72, v72
	v_exp_f32_e32 v73, v73
	v_pk_mul_f32 v[50:51], v[50:51], v[66:67]
	v_pk_mul_f32 v[52:53], v[52:53], v[68:69]
	v_add_f32_e32 v70, 1.0, v70
	v_add_f32_e32 v71, 1.0, v71
	v_add_f32_e32 v72, 1.0, v72
	v_add_f32_e32 v73, 1.0, v73
	v_rcp_f32_e32 v70, v70
	v_rcp_f32_e32 v71, v71
	v_rcp_f32_e32 v72, v72
	v_rcp_f32_e32 v73, v73
	v_pk_mul_f32 v[50:51], v[50:51], v[70:71]
	v_pk_mul_f32 v[52:53], v[52:53], v[72:73]
	v_cvt_pk_bf16_f32 v50, v50, v51
	v_cvt_pk_bf16_f32 v51, v52, v53
	s_waitcnt vmcnt(15)
	v_lshlrev_b32_e32 v74, 16, v194
	v_and_b32_e32 v75, 0xffff0000, v194
	v_lshlrev_b32_e32 v76, 16, v195
	v_and_b32_e32 v77, 0xffff0000, v195
	v_mul_f32_e32 v78, 0xbfb8aa3b, v74
	v_mul_f32_e32 v79, 0xbfb8aa3b, v75
	v_mul_f32_e32 v80, 0xbfb8aa3b, v76
	v_mul_f32_e32 v81, 0xbfb8aa3b, v77
	v_exp_f32_e32 v78, v78
	v_exp_f32_e32 v79, v79
	v_exp_f32_e32 v80, v80
	v_exp_f32_e32 v81, v81
	v_pk_mul_f32 v[54:55], v[54:55], v[74:75]
	v_pk_mul_f32 v[56:57], v[56:57], v[76:77]
	v_add_f32_e32 v78, 1.0, v78
	v_add_f32_e32 v79, 1.0, v79
	v_add_f32_e32 v80, 1.0, v80
	v_add_f32_e32 v81, 1.0, v81
	v_rcp_f32_e32 v78, v78
	v_rcp_f32_e32 v79, v79
	v_rcp_f32_e32 v80, v80
	v_rcp_f32_e32 v81, v81
	v_pk_mul_f32 v[54:55], v[54:55], v[78:79]
	v_pk_mul_f32 v[56:57], v[56:57], v[80:81]
	v_cvt_pk_bf16_f32 v54, v54, v55
	v_cvt_pk_bf16_f32 v55, v56, v57
	s_waitcnt vmcnt(14)
	v_lshlrev_b32_e32 v66, 16, v196
	v_and_b32_e32 v67, 0xffff0000, v196
	v_lshlrev_b32_e32 v68, 16, v197
	v_and_b32_e32 v69, 0xffff0000, v197
	v_mul_f32_e32 v70, 0xbfb8aa3b, v66
	v_mul_f32_e32 v71, 0xbfb8aa3b, v67
	v_mul_f32_e32 v72, 0xbfb8aa3b, v68
	v_mul_f32_e32 v73, 0xbfb8aa3b, v69
	v_exp_f32_e32 v70, v70
	v_exp_f32_e32 v71, v71
	v_exp_f32_e32 v72, v72
	v_exp_f32_e32 v73, v73
	v_pk_mul_f32 v[58:59], v[58:59], v[66:67]
	v_pk_mul_f32 v[60:61], v[60:61], v[68:69]
	v_add_f32_e32 v70, 1.0, v70
	v_add_f32_e32 v71, 1.0, v71
	v_add_f32_e32 v72, 1.0, v72
	v_add_f32_e32 v73, 1.0, v73
	v_rcp_f32_e32 v70, v70
	v_rcp_f32_e32 v71, v71
	v_rcp_f32_e32 v72, v72
	v_rcp_f32_e32 v73, v73
	v_pk_mul_f32 v[58:59], v[58:59], v[70:71]
	v_pk_mul_f32 v[60:61], v[60:61], v[72:73]
	v_cvt_pk_bf16_f32 v58, v58, v59
	v_cvt_pk_bf16_f32 v59, v60, v61
	s_waitcnt vmcnt(13)
	v_lshlrev_b32_e32 v74, 16, v198
	v_and_b32_e32 v75, 0xffff0000, v198
	v_lshlrev_b32_e32 v76, 16, v199
	v_and_b32_e32 v77, 0xffff0000, v199
	v_mul_f32_e32 v78, 0xbfb8aa3b, v74
	v_mul_f32_e32 v79, 0xbfb8aa3b, v75
	v_mul_f32_e32 v80, 0xbfb8aa3b, v76
	v_mul_f32_e32 v81, 0xbfb8aa3b, v77
	v_exp_f32_e32 v78, v78
	v_exp_f32_e32 v79, v79
	v_exp_f32_e32 v80, v80
	v_exp_f32_e32 v81, v81
	v_pk_mul_f32 v[62:63], v[62:63], v[74:75]
	v_pk_mul_f32 v[64:65], v[64:65], v[76:77]
	v_add_f32_e32 v78, 1.0, v78
	v_add_f32_e32 v79, 1.0, v79
	v_add_f32_e32 v80, 1.0, v80
	v_add_f32_e32 v81, 1.0, v81
	v_rcp_f32_e32 v78, v78
	v_rcp_f32_e32 v79, v79
	v_rcp_f32_e32 v80, v80
	v_rcp_f32_e32 v81, v81
	v_pk_mul_f32 v[62:63], v[62:63], v[78:79]
	v_pk_mul_f32 v[64:65], v[64:65], v[80:81]
	v_cvt_pk_bf16_f32 v62, v62, v63
	v_cvt_pk_bf16_f32 v63, v64, v65
	s_waitcnt vmcnt(12)
; DI unsigned pk2(float a, float b) { f32x2 v = {a, b}; bf16v2 r = __builtin_convertvector(v, bf16v2); return __builtin_bit_cast(unsigned, r); }
; DI float bf_lo(unsigned u) { return __uint_as_float(u << 16); }
; DI float bf_hi(unsigned u) { return __uint_as_float(u & 0xffff0000u); }
; DI float silu_mul(float o, float g) { return o * g * __builtin_amdgcn_rcpf(1.0f + __builtin_amdgcn_exp2f(g * -1.4426950408889634f)); }
; DI void attnB_item(bf16_t* z, int hh, int qs, LAS bf16_t* vs, int lane) {
;     ...
;             for (int g = 0; g < 4; ++g) {
;                 const int d0 = (dt << 9) | (g << 7);
;                 const u32x2 gv = *(const u32x2*)(grow + d0);
;                 u32x2 o; o.x = pk2(silu_mul(acc[dt][4 * g], bf_lo(gv.x)), silu_mul(acc[dt][4 * g + 1], bf_hi(gv.x)));
;                 o.y = pk2(silu_mul(acc[dt][4 * g + 2], bf_lo(gv.y)), silu_mul(acc[dt][4 * g + 3], bf_hi(gv.y)));
;                 *(u32x2*)(orow + d0) = o;
	v_lshlrev_b32_e32 v66, 16, v200
	v_and_b32_e32 v67, 0xffff0000, v200
	v_lshlrev_b32_e32 v68, 16, v201
	v_and_b32_e32 v69, 0xffff0000, v201
	v_mul_f32_e32 v70, 0xbfb8aa3b, v66
	v_mul_f32_e32 v71, 0xbfb8aa3b, v67
	v_mul_f32_e32 v72, 0xbfb8aa3b, v68
	v_mul_f32_e32 v73, 0xbfb8aa3b, v69
	v_exp_f32_e32 v70, v70
	v_exp_f32_e32 v71, v71
	v_exp_f32_e32 v72, v72
	v_exp_f32_e32 v73, v73
	v_pk_mul_f32 v[34:35], v[34:35], v[66:67]
	v_pk_mul_f32 v[36:37], v[36:37], v[68:69]
	v_add_f32_e32 v70, 1.0, v70
	v_add_f32_e32 v71, 1.0, v71
	v_add_f32_e32 v72, 1.0, v72
	v_add_f32_e32 v73, 1.0, v73
	v_rcp_f32_e32 v70, v70
	v_rcp_f32_e32 v71, v71
	v_rcp_f32_e32 v72, v72
	v_rcp_f32_e32 v73, v73
	v_pk_mul_f32 v[34:35], v[34:35], v[70:71]
	v_pk_mul_f32 v[36:37], v[36:37], v[72:73]
	v_cvt_pk_bf16_f32 v34, v34, v35
	v_cvt_pk_bf16_f32 v35, v36, v37
	s_waitcnt vmcnt(11)
	v_lshlrev_b32_e32 v74, 16, v202
	v_and_b32_e32 v75, 0xffff0000, v202
	v_lshlrev_b32_e32 v76, 16, v203
	v_and_b32_e32 v77, 0xffff0000, v203
	v_mul_f32_e32 v78, 0xbfb8aa3b, v74
	v_mul_f32_e32 v79, 0xbfb8aa3b, v75
	v_mul_f32_e32 v80, 0xbfb8aa3b, v76
	v_mul_f32_e32 v81, 0xbfb8aa3b, v77
	v_exp_f32_e32 v78, v78
	v_exp_f32_e32 v79, v79
	v_exp_f32_e32 v80, v80
	v_exp_f32_e32 v81, v81
	v_pk_mul_f32 v[38:39], v[38:39], v[74:75]
	v_pk_mul_f32 v[40:41], v[40:41], v[76:77]
	v_add_f32_e32 v78, 1.0, v78
	v_add_f32_e32 v79, 1.0, v79
	v_add_f32_e32 v80, 1.0, v80
	v_add_f32_e32 v81, 1.0, v81
	v_rcp_f32_e32 v78, v78
	v_rcp_f32_e32 v79, v79
	v_rcp_f32_e32 v80, v80
	v_rcp_f32_e32 v81, v81
	v_pk_mul_f32 v[38:39], v[38:39], v[78:79]
	v_pk_mul_f32 v[40:41], v[40:41], v[80:81]
	v_cvt_pk_bf16_f32 v38, v38, v39
	v_cvt_pk_bf16_f32 v39, v40, v41
	s_waitcnt vmcnt(10)
	v_lshlrev_b32_e32 v66, 16, v204
	v_and_b32_e32 v67, 0xffff0000, v204
	v_lshlrev_b32_e32 v68, 16, v205
	v_and_b32_e32 v69, 0xffff0000, v205
	v_mul_f32_e32 v70, 0xbfb8aa3b, v66
	v_mul_f32_e32 v71, 0xbfb8aa3b, v67
	v_mul_f32_e32 v72, 0xbfb8aa3b, v68
	v_mul_f32_e32 v73, 0xbfb8aa3b, v69
	v_exp_f32_e32 v70, v70
	v_exp_f32_e32 v71, v71
	v_exp_f32_e32 v72, v72
	v_exp_f32_e32 v73, v73
	v_pk_mul_f32 v[42:43], v[42:43], v[66:67]
	v_pk_mul_f32 v[44:45], v[44:45], v[68:69]
	v_add_f32_e32 v70, 1.0, v70
	v_add_f32_e32 v71, 1.0, v71
	v_add_f32_e32 v72, 1.0, v72
	v_add_f32_e32 v73, 1.0, v73
	v_rcp_f32_e32 v70, v70
	v_rcp_f32_e32 v71, v71
	v_rcp_f32_e32 v72, v72
	v_rcp_f32_e32 v73, v73
	v_pk_mul_f32 v[42:43], v[42:43], v[70:71]
	v_pk_mul_f32 v[44:45], v[44:45], v[72:73]
	v_cvt_pk_bf16_f32 v42, v42, v43
	v_cvt_pk_bf16_f32 v43, v44, v45
	s_waitcnt vmcnt(9)
	v_lshlrev_b32_e32 v74, 16, v206
	v_and_b32_e32 v75, 0xffff0000, v206
	v_lshlrev_b32_e32 v76, 16, v207
	v_and_b32_e32 v77, 0xffff0000, v207
	v_mul_f32_e32 v78, 0xbfb8aa3b, v74
	v_mul_f32_e32 v79, 0xbfb8aa3b, v75
	v_mul_f32_e32 v80, 0xbfb8aa3b, v76
	v_mul_f32_e32 v81, 0xbfb8aa3b, v77
	v_exp_f32_e32 v78, v78
	v_exp_f32_e32 v79, v79
	v_exp_f32_e32 v80, v80
	v_exp_f32_e32 v81, v81
	v_pk_mul_f32 v[46:47], v[46:47], v[74:75]
	v_pk_mul_f32 v[48:49], v[48:49], v[76:77]
	v_add_f32_e32 v78, 1.0, v78
	v_add_f32_e32 v79, 1.0, v79
	v_add_f32_e32 v80, 1.0, v80
	v_add_f32_e32 v81, 1.0, v81
	v_rcp_f32_e32 v78, v78
	v_rcp_f32_e32 v79, v79
	v_rcp_f32_e32 v80, v80
	v_rcp_f32_e32 v81, v81
	v_pk_mul_f32 v[46:47], v[46:47], v[78:79]
	v_pk_mul_f32 v[48:49], v[48:49], v[80:81]
	v_cvt_pk_bf16_f32 v46, v46, v47
	v_cvt_pk_bf16_f32 v47, v48, v49
	s_waitcnt vmcnt(8)
	v_lshlrev_b32_e32 v66, 16, v208
	v_and_b32_e32 v67, 0xffff0000, v208
	v_lshlrev_b32_e32 v68, 16, v209
	v_and_b32_e32 v69, 0xffff0000, v209
	v_mul_f32_e32 v70, 0xbfb8aa3b, v66
	v_mul_f32_e32 v71, 0xbfb8aa3b, v67
	v_mul_f32_e32 v72, 0xbfb8aa3b, v68
	v_mul_f32_e32 v73, 0xbfb8aa3b, v69
	v_exp_f32_e32 v70, v70
	v_exp_f32_e32 v71, v71
	v_exp_f32_e32 v72, v72
	v_exp_f32_e32 v73, v73
	v_pk_mul_f32 v[18:19], v[18:19], v[66:67]
	v_pk_mul_f32 v[20:21], v[20:21], v[68:69]
	v_add_f32_e32 v70, 1.0, v70
	v_add_f32_e32 v71, 1.0, v71
	v_add_f32_e32 v72, 1.0, v72
	v_add_f32_e32 v73, 1.0, v73
	v_rcp_f32_e32 v70, v70
	v_rcp_f32_e32 v71, v71
	v_rcp_f32_e32 v72, v72
	v_rcp_f32_e32 v73, v73
	v_pk_mul_f32 v[18:19], v[18:19], v[70:71]
	v_pk_mul_f32 v[20:21], v[20:21], v[72:73]
	v_cvt_pk_bf16_f32 v18, v18, v19
	v_cvt_pk_bf16_f32 v19, v20, v21
	s_waitcnt vmcnt(7)
	v_lshlrev_b32_e32 v74, 16, v210
	v_and_b32_e32 v75, 0xffff0000, v210
	v_lshlrev_b32_e32 v76, 16, v211
	v_and_b32_e32 v77, 0xffff0000, v211
	v_mul_f32_e32 v78, 0xbfb8aa3b, v74
	v_mul_f32_e32 v79, 0xbfb8aa3b, v75
	v_mul_f32_e32 v80, 0xbfb8aa3b, v76
	v_mul_f32_e32 v81, 0xbfb8aa3b, v77
	v_exp_f32_e32 v78, v78
	v_exp_f32_e32 v79, v79
	v_exp_f32_e32 v80, v80
	v_exp_f32_e32 v81, v81
	v_pk_mul_f32 v[22:23], v[22:23], v[74:75]
	v_pk_mul_f32 v[24:25], v[24:25], v[76:77]
	v_add_f32_e32 v78, 1.0, v78
	v_add_f32_e32 v79, 1.0, v79
	v_add_f32_e32 v80, 1.0, v80
	v_add_f32_e32 v81, 1.0, v81
	v_rcp_f32_e32 v78, v78
	v_rcp_f32_e32 v79, v79
	v_rcp_f32_e32 v80, v80
	v_rcp_f32_e32 v81, v81
	v_pk_mul_f32 v[22:23], v[22:23], v[78:79]
	v_pk_mul_f32 v[24:25], v[24:25], v[80:81]
	v_cvt_pk_bf16_f32 v22, v22, v23
	v_cvt_pk_bf16_f32 v23, v24, v25
	s_waitcnt vmcnt(6)
	v_lshlrev_b32_e32 v66, 16, v212
	v_and_b32_e32 v67, 0xffff0000, v212
	v_lshlrev_b32_e32 v68, 16, v213
	v_and_b32_e32 v69, 0xffff0000, v213
	v_mul_f32_e32 v70, 0xbfb8aa3b, v66
	v_mul_f32_e32 v71, 0xbfb8aa3b, v67
	v_mul_f32_e32 v72, 0xbfb8aa3b, v68
	v_mul_f32_e32 v73, 0xbfb8aa3b, v69
	v_exp_f32_e32 v70, v70
	v_exp_f32_e32 v71, v71
	v_exp_f32_e32 v72, v72
	v_exp_f32_e32 v73, v73
	v_pk_mul_f32 v[26:27], v[26:27], v[66:67]
	v_pk_mul_f32 v[28:29], v[28:29], v[68:69]
	v_add_f32_e32 v70, 1.0, v70
	v_add_f32_e32 v71, 1.0, v71
	v_add_f32_e32 v72, 1.0, v72
	v_add_f32_e32 v73, 1.0, v73
	v_rcp_f32_e32 v70, v70
	v_rcp_f32_e32 v71, v71
	v_rcp_f32_e32 v72, v72
	v_rcp_f32_e32 v73, v73
	v_pk_mul_f32 v[26:27], v[26:27], v[70:71]
	v_pk_mul_f32 v[28:29], v[28:29], v[72:73]
	v_cvt_pk_bf16_f32 v26, v26, v27
	v_cvt_pk_bf16_f32 v27, v28, v29
	s_waitcnt vmcnt(5)
; DI unsigned pk2(float a, float b) { f32x2 v = {a, b}; bf16v2 r = __builtin_convertvector(v, bf16v2); return __builtin_bit_cast(unsigned, r); }
; DI float bf_lo(unsigned u) { return __uint_as_float(u << 16); }
; DI float bf_hi(unsigned u) { return __uint_as_float(u & 0xffff0000u); }
; DI float silu_mul(float o, float g) { return o * g * __builtin_amdgcn_rcpf(1.0f + __builtin_amdgcn_exp2f(g * -1.4426950408889634f)); }
; DI void attnB_item(bf16_t* z, int hh, int qs, LAS bf16_t* vs, int lane) {
;     ...
;             for (int g = 0; g < 4; ++g) {
;                 const int d0 = (dt << 9) | (g << 7);
;                 const u32x2 gv = *(const u32x2*)(grow + d0);
;                 u32x2 o; o.x = pk2(silu_mul(acc[dt][4 * g], bf_lo(gv.x)), silu_mul(acc[dt][4 * g + 1], bf_hi(gv.x)));
;                 o.y = pk2(silu_mul(acc[dt][4 * g + 2], bf_lo(gv.y)), silu_mul(acc[dt][4 * g + 3], bf_hi(gv.y)));
;                 *(u32x2*)(orow + d0) = o;
;             }
	v_lshlrev_b32_e32 v74, 16, v214
	v_and_b32_e32 v75, 0xffff0000, v214
	v_lshlrev_b32_e32 v76, 16, v215
	v_and_b32_e32 v77, 0xffff0000, v215
	v_mul_f32_e32 v78, 0xbfb8aa3b, v74
	v_mul_f32_e32 v79, 0xbfb8aa3b, v75
	v_mul_f32_e32 v80, 0xbfb8aa3b, v76
	v_mul_f32_e32 v81, 0xbfb8aa3b, v77
	v_exp_f32_e32 v78, v78
	v_exp_f32_e32 v79, v79
	v_exp_f32_e32 v80, v80
	v_exp_f32_e32 v81, v81
	v_pk_mul_f32 v[30:31], v[30:31], v[74:75]
	v_pk_mul_f32 v[32:33], v[32:33], v[76:77]
	v_add_f32_e32 v78, 1.0, v78
	v_add_f32_e32 v79, 1.0, v79
	v_add_f32_e32 v80, 1.0, v80
	v_add_f32_e32 v81, 1.0, v81
	v_rcp_f32_e32 v78, v78
	v_rcp_f32_e32 v79, v79
	v_rcp_f32_e32 v80, v80
	v_rcp_f32_e32 v81, v81
	v_pk_mul_f32 v[30:31], v[30:31], v[78:79]
	v_pk_mul_f32 v[32:33], v[32:33], v[80:81]
	v_cvt_pk_bf16_f32 v30, v30, v31
	v_cvt_pk_bf16_f32 v31, v32, v33
	s_waitcnt vmcnt(4)
	v_lshlrev_b32_e32 v66, 16, v216
	v_and_b32_e32 v67, 0xffff0000, v216
	v_lshlrev_b32_e32 v68, 16, v217
	v_and_b32_e32 v69, 0xffff0000, v217
	v_mul_f32_e32 v70, 0xbfb8aa3b, v66
	v_mul_f32_e32 v71, 0xbfb8aa3b, v67
	v_mul_f32_e32 v72, 0xbfb8aa3b, v68
	v_mul_f32_e32 v73, 0xbfb8aa3b, v69
	v_exp_f32_e32 v70, v70
	v_exp_f32_e32 v71, v71
	v_exp_f32_e32 v72, v72
	v_exp_f32_e32 v73, v73
	v_pk_mul_f32 v[2:3], v[2:3], v[66:67]
	v_pk_mul_f32 v[4:5], v[4:5], v[68:69]
	v_add_f32_e32 v70, 1.0, v70
	v_add_f32_e32 v71, 1.0, v71
	v_add_f32_e32 v72, 1.0, v72
	v_add_f32_e32 v73, 1.0, v73
	v_rcp_f32_e32 v70, v70
	v_rcp_f32_e32 v71, v71
	v_rcp_f32_e32 v72, v72
	v_rcp_f32_e32 v73, v73
	v_pk_mul_f32 v[2:3], v[2:3], v[70:71]
	v_pk_mul_f32 v[4:5], v[4:5], v[72:73]
	v_cvt_pk_bf16_f32 v2, v2, v3
	v_cvt_pk_bf16_f32 v3, v4, v5
	s_waitcnt vmcnt(3)
	v_lshlrev_b32_e32 v74, 16, v218
	v_and_b32_e32 v75, 0xffff0000, v218
	v_lshlrev_b32_e32 v76, 16, v219
	v_and_b32_e32 v77, 0xffff0000, v219
	v_mul_f32_e32 v78, 0xbfb8aa3b, v74
	v_mul_f32_e32 v79, 0xbfb8aa3b, v75
	v_mul_f32_e32 v80, 0xbfb8aa3b, v76
	v_mul_f32_e32 v81, 0xbfb8aa3b, v77
	v_exp_f32_e32 v78, v78
	v_exp_f32_e32 v79, v79
	v_exp_f32_e32 v80, v80
	v_exp_f32_e32 v81, v81
	v_pk_mul_f32 v[6:7], v[6:7], v[74:75]
	v_pk_mul_f32 v[8:9], v[8:9], v[76:77]
	v_add_f32_e32 v78, 1.0, v78
	v_add_f32_e32 v79, 1.0, v79
	v_add_f32_e32 v80, 1.0, v80
	v_add_f32_e32 v81, 1.0, v81
	v_rcp_f32_e32 v78, v78
	v_rcp_f32_e32 v79, v79
	v_rcp_f32_e32 v80, v80
	v_rcp_f32_e32 v81, v81
	v_pk_mul_f32 v[6:7], v[6:7], v[78:79]
	v_pk_mul_f32 v[8:9], v[8:9], v[80:81]
	v_cvt_pk_bf16_f32 v6, v6, v7
	v_cvt_pk_bf16_f32 v7, v8, v9
	s_waitcnt vmcnt(2)
	v_lshlrev_b32_e32 v66, 16, v220
	v_and_b32_e32 v67, 0xffff0000, v220
	v_lshlrev_b32_e32 v68, 16, v221
	v_and_b32_e32 v69, 0xffff0000, v221
	v_mul_f32_e32 v70, 0xbfb8aa3b, v66
	v_mul_f32_e32 v71, 0xbfb8aa3b, v67
	v_mul_f32_e32 v72, 0xbfb8aa3b, v68
	v_mul_f32_e32 v73, 0xbfb8aa3b, v69
	v_exp_f32_e32 v70, v70
	v_exp_f32_e32 v71, v71
	v_exp_f32_e32 v72, v72
	v_exp_f32_e32 v73, v73
	v_pk_mul_f32 v[10:11], v[10:11], v[66:67]
	v_pk_mul_f32 v[12:13], v[12:13], v[68:69]
	v_add_f32_e32 v70, 1.0, v70
	v_add_f32_e32 v71, 1.0, v71
	v_add_f32_e32 v72, 1.0, v72
	v_add_f32_e32 v73, 1.0, v73
	v_rcp_f32_e32 v70, v70
	v_rcp_f32_e32 v71, v71
	v_rcp_f32_e32 v72, v72
	v_rcp_f32_e32 v73, v73
	v_pk_mul_f32 v[10:11], v[10:11], v[70:71]
	v_pk_mul_f32 v[12:13], v[12:13], v[72:73]
	v_cvt_pk_bf16_f32 v10, v10, v11
	v_cvt_pk_bf16_f32 v11, v12, v13
	s_waitcnt vmcnt(1)
	v_lshlrev_b32_e32 v74, 16, v222
	v_and_b32_e32 v75, 0xffff0000, v222
	v_lshlrev_b32_e32 v76, 16, v223
	v_and_b32_e32 v77, 0xffff0000, v223
	v_mul_f32_e32 v78, 0xbfb8aa3b, v74
	v_mul_f32_e32 v79, 0xbfb8aa3b, v75
	v_mul_f32_e32 v80, 0xbfb8aa3b, v76
	v_mul_f32_e32 v81, 0xbfb8aa3b, v77
	v_exp_f32_e32 v78, v78
	v_exp_f32_e32 v79, v79
	v_exp_f32_e32 v80, v80
	v_exp_f32_e32 v81, v81
	v_pk_mul_f32 v[14:15], v[14:15], v[74:75]
	v_pk_mul_f32 v[16:17], v[16:17], v[76:77]
	v_add_f32_e32 v78, 1.0, v78
	v_add_f32_e32 v79, 1.0, v79
	v_add_f32_e32 v80, 1.0, v80
	v_add_f32_e32 v81, 1.0, v81
	v_rcp_f32_e32 v78, v78
	v_rcp_f32_e32 v79, v79
	v_rcp_f32_e32 v80, v80
	v_rcp_f32_e32 v81, v81
	v_pk_mul_f32 v[14:15], v[14:15], v[78:79]
	v_pk_mul_f32 v[16:17], v[16:17], v[80:81]
	v_cvt_pk_bf16_f32 v14, v14, v15
	v_cvt_pk_bf16_f32 v15, v16, v17
	global_store_dwordx2 v[146:147], v[50:51], off nt
	global_store_dwordx2 v[146:147], v[54:55], off offset:256 nt
	global_store_dwordx2 v[146:147], v[58:59], off offset:512 nt
	global_store_dwordx2 v[146:147], v[62:63], off offset:768 nt
	global_store_dwordx2 v[146:147], v[34:35], off offset:1024 nt
	global_store_dwordx2 v[146:147], v[38:39], off offset:1280 nt
	global_store_dwordx2 v[146:147], v[42:43], off offset:1536 nt
	global_store_dwordx2 v[146:147], v[46:47], off offset:1792 nt
	global_store_dwordx2 v[146:147], v[18:19], off offset:2048 nt
	global_store_dwordx2 v[146:147], v[22:23], off offset:2304 nt
	global_store_dwordx2 v[146:147], v[26:27], off offset:2560 nt
	global_store_dwordx2 v[146:147], v[30:31], off offset:2816 nt
	global_store_dwordx2 v[146:147], v[2:3], off offset:3072 nt
	global_store_dwordx2 v[146:147], v[6:7], off offset:3328 nt
	global_store_dwordx2 v[146:147], v[10:11], off offset:3584 nt
	global_store_dwordx2 v[146:147], v[14:15], off offset:3840 nt
	s_branch .LBB0_130

; DI unsigned pk2(float a, float b) { f32x2 v = {a, b}; bf16v2 r = __builtin_convertvector(v, bf16v2); return __builtin_bit_cast(unsigned, r); }
; DI float bf_lo(unsigned u) { return __uint_as_float(u << 16); }
; DI float bf_hi(unsigned u) { return __uint_as_float(u & 0xffff0000u); }
; DI size_t zrowU(int row0, int NT) { return ((size_t)((row0 >> 8) * NT) << 16) + (size_t)((((row0 >> 7) & 1) << 15) | (((row0 >> 5) & 1) << 14) | (((row0 >> 6) & 1) << 11)); }
; DI unsigned zlaneRC(int r5, int col) { return (unsigned)(((col >> 8) << 16) | ((r5 >> 4) << 13) | (((col >> 7) & 1) << 12) | (((col >> 5) & 3) << 9) | (((col >> 3) & 3) << 7) | ((r5 & 15) << 3) | (col & 7)); }
; DI float silu_mul(float o, float g) { return o * g * __builtin_amdgcn_rcpf(1.0f + __builtin_amdgcn_exp2f(g * -1.4426950408889634f)); }
; DI void attnA_item(bf16_t* z, const float* sinks, int hp, int qs, LAS bf16_t* vs, const LAS float* btab, int lane) {
;     ...
;     if (!metaq || c < NMETA) {
; #pragma unroll
;         for (int u = 0; u < 2; ++u) {
;             const float inv = 1.0f / l[u];
;             bf16_t* orow = z + zrowU(qrow0, 18) + zlaneRC(c, (2 * hp + u) * 64 + 4 * h);
;             const bf16_t* grow = z + zrowU(qrow0, 18) + zlaneRC(c, 2560 + (2 * hp + u) * 64 + 4 * h);
; #pragma unroll
;             for (int dt = 0; dt < 2; ++dt)
; #pragma unroll
;                 for (int g = 0; g < 4; ++g) {
;                     const int d0 = (dt << 9) | (g << 7);
;                     const u32x2 gv = *(const u32x2*)(grow + d0);
;                     u32x2 o; o.x = pk2(silu_mul(acc[u][dt][4 * g] * inv, bf_lo(gv.x)), silu_mul(acc[u][dt][4 * g + 1] * inv, bf_hi(gv.x)));
;                     o.y = pk2(silu_mul(acc[u][dt][4 * g + 2] * inv, bf_lo(gv.y)), silu_mul(acc[u][dt][4 * g + 3] * inv, bf_hi(gv.y)));
.LBB0_211:
	v_cmp_gt_u32_e32 vcc, 16, v127
	s_xor_b64 s[4:5], s[68:69], -1
	s_or_b64 s[4:5], s[4:5], vcc
	s_and_saveexec_b64 s[6:7], s[4:5]
	s_xor_b64 s[36:37], exec, s[6:7]
	s_cbranch_execz .LBB0_177
	v_div_scale_f32 v0, s[4:5], v75, v75, 1.0
	v_rcp_f32_e32 v130, v0
	v_and_b32_e32 v134, 4, v125
	v_add_u32_e32 v135, 0xa00, v125
	v_fma_f32 v148, -v0, v130, 1.0
	v_fmac_f32_e32 v130, v148, v130
	v_div_scale_f32 v148, vcc, 1.0, v75, 1.0
	v_mul_f32_e32 v149, v148, v130
	v_fma_f32 v150, -v0, v149, v148
	v_fmac_f32_e32 v149, v150, v130
	v_fma_f32 v0, -v0, v149, v148
	v_div_fmas_f32 v0, v0, v130, v149
	v_div_fixup_f32 v130, v0, v75, 1.0
	v_add_u32_e32 v0, s27, v125
	v_lshlrev_b32_e32 v136, 8, v0
	v_lshlrev_b32_e32 v0, 5, v0
	v_lshlrev_b32_e32 v137, 6, v126
	v_and_b32_e32 v136, 0xffff0000, v136
	v_and_b32_e32 v0, 0x1000, v0
	v_and_b32_e32 v146, 0x780, v137
	v_or3_b32 v0, v0, v136, v146
	v_or3_b32 v0, v0, v134, v124
	v_lshl_add_u64 v[138:139], v[0:1], 1, s[0:1]
	v_add_u32_e32 v0, s27, v135
	v_lshlrev_b32_e32 v147, 8, v0
	v_lshlrev_b32_e32 v0, 5, v0
	v_and_b32_e32 v147, 0xffff0000, v147
	v_and_b32_e32 v0, 0x1000, v0
	v_or3_b32 v0, v0, v147, v146
	v_or3_b32 v0, v0, v134, v124
	v_lshl_add_u64 v[140:141], v[0:1], 1, s[0:1]
	global_load_dwordx2 v[178:179], v[140:141], off
	global_load_dwordx2 v[180:181], v[140:141], off offset:256
	global_load_dwordx2 v[182:183], v[140:141], off offset:512
	global_load_dwordx2 v[184:185], v[140:141], off offset:768
	global_load_dwordx2 v[186:187], v[140:141], off offset:1024
	global_load_dwordx2 v[188:189], v[140:141], off offset:1280
	global_load_dwordx2 v[190:191], v[140:141], off offset:1536
	global_load_dwordx2 v[192:193], v[140:141], off offset:1792
	v_div_scale_f32 v0, s[4:5], v74, v74, 1.0
	s_or_b32 s4, s27, 64
	v_rcp_f32_e32 v132, v0
	s_nop 0
	v_fma_f32 v148, -v0, v132, 1.0
	v_fmac_f32_e32 v132, v148, v132
	v_div_scale_f32 v148, vcc, 1.0, v74, 1.0
	v_mul_f32_e32 v149, v148, v132
	v_fma_f32 v150, -v0, v149, v148
	v_fmac_f32_e32 v149, v150, v132
	v_fma_f32 v0, -v0, v149, v148
	v_div_fmas_f32 v0, v0, v132, v149
	v_div_fixup_f32 v132, v0, v74, 1.0
	v_add_u32_e32 v0, s4, v125
	v_lshlrev_b32_e32 v136, 8, v0
	v_lshlrev_b32_e32 v137, 5, v0
	v_lshlrev_b32_e32 v0, 4, v0
	v_and_b32_e32 v136, 0xffff0000, v136
	v_and_b32_e32 v137, 0x1000, v137
	v_and_b32_e32 v0, 0x780, v0
	v_or3_b32 v0, v137, v136, v0
	v_or3_b32 v0, v0, v134, v124
	v_lshl_add_u64 v[142:143], v[0:1], 1, s[0:1]
	v_add_u32_e32 v0, s4, v135
	v_lshlrev_b32_e32 v136, 8, v0
	v_lshlrev_b32_e32 v147, 5, v0
	v_lshlrev_b32_e32 v0, 4, v0
	v_and_b32_e32 v136, 0xffff0000, v136
	v_and_b32_e32 v147, 0x1000, v147
	v_and_b32_e32 v0, 0x780, v0
	v_or3_b32 v0, v147, v136, v0
	v_or3_b32 v0, v0, v134, v124
	v_lshl_add_u64 v[144:145], v[0:1], 1, s[0:1]
	global_load_dwordx2 v[194:195], v[144:145], off
	global_load_dwordx2 v[196:197], v[144:145], off offset:256
	global_load_dwordx2 v[198:199], v[144:145], off offset:512
	global_load_dwordx2 v[200:201], v[144:145], off offset:768
	global_load_dwordx2 v[202:203], v[144:145], off offset:1024
	global_load_dwordx2 v[204:205], v[144:145], off offset:1280
	global_load_dwordx2 v[206:207], v[144:145], off offset:1536
	global_load_dwordx2 v[208:209], v[144:145], off offset:1792
	s_add_i32 s5, s26, s33
	s_and_b32 s5, s5, 7
	s_lshl_b32 s5, s5, 8
	s_mov_b64 vcc, exec
	s_mov_b64 exec, 1
	v_mov_b32_e32 v210, s5
	v_mov_b32_e32 v211, 1
	global_atomic_add v240, v210, v211, s[34:35] sc0
	s_mov_b64 exec, vcc
	s_mov_b32 s100, 1
	v_pk_mul_f32 v[50:51], v[130:131], v[50:51] op_sel_hi:[0,1]
	v_pk_mul_f32 v[52:53], v[130:131], v[52:53] op_sel_hi:[0,1]
	v_pk_mul_f32 v[54:55], v[130:131], v[54:55] op_sel_hi:[0,1]
	v_pk_mul_f32 v[56:57], v[130:131], v[56:57] op_sel_hi:[0,1]
	v_pk_mul_f32 v[58:59], v[130:131], v[58:59] op_sel_hi:[0,1]
	v_pk_mul_f32 v[60:61], v[130:131], v[60:61] op_sel_hi:[0,1]
	v_pk_mul_f32 v[62:63], v[130:131], v[62:63] op_sel_hi:[0,1]
	v_pk_mul_f32 v[64:65], v[130:131], v[64:65] op_sel_hi:[0,1]
	v_pk_mul_f32 v[34:35], v[130:131], v[34:35] op_sel_hi:[0,1]
	v_pk_mul_f32 v[36:37], v[130:131], v[36:37] op_sel_hi:[0,1]
	v_pk_mul_f32 v[38:39], v[130:131], v[38:39] op_sel_hi:[0,1]
	v_pk_mul_f32 v[40:41], v[130:131], v[40:41] op_sel_hi:[0,1]
	v_pk_mul_f32 v[42:43], v[130:131], v[42:43] op_sel_hi:[0,1]
	v_pk_mul_f32 v[44:45], v[130:131], v[44:45] op_sel_hi:[0,1]
	v_pk_mul_f32 v[46:47], v[130:131], v[46:47] op_sel_hi:[0,1]
	v_pk_mul_f32 v[48:49], v[130:131], v[48:49] op_sel_hi:[0,1]
	v_pk_mul_f32 v[18:19], v[132:133], v[18:19] op_sel_hi:[0,1]
	v_pk_mul_f32 v[20:21], v[132:133], v[20:21] op_sel_hi:[0,1]
	v_pk_mul_f32 v[22:23], v[132:133], v[22:23] op_sel_hi:[0,1]
	v_pk_mul_f32 v[24:25], v[132:133], v[24:25] op_sel_hi:[0,1]
	v_pk_mul_f32 v[26:27], v[132:133], v[26:27] op_sel_hi:[0,1]
	v_pk_mul_f32 v[28:29], v[132:133], v[28:29] op_sel_hi:[0,1]
	v_pk_mul_f32 v[30:31], v[132:133], v[30:31] op_sel_hi:[0,1]
	v_pk_mul_f32 v[32:33], v[132:133], v[32:33] op_sel_hi:[0,1]
	v_pk_mul_f32 v[2:3], v[132:133], v[2:3] op_sel_hi:[0,1]
	v_pk_mul_f32 v[4:5], v[132:133], v[4:5] op_sel_hi:[0,1]
	v_pk_mul_f32 v[6:7], v[132:133], v[6:7] op_sel_hi:[0,1]
	v_pk_mul_f32 v[8:9], v[132:133], v[8:9] op_sel_hi:[0,1]
	v_pk_mul_f32 v[10:11], v[132:133], v[10:11] op_sel_hi:[0,1]
	v_pk_mul_f32 v[12:13], v[132:133], v[12:13] op_sel_hi:[0,1]
	v_pk_mul_f32 v[14:15], v[132:133], v[14:15] op_sel_hi:[0,1]
	v_pk_mul_f32 v[16:17], v[132:133], v[16:17] op_sel_hi:[0,1]
	s_waitcnt vmcnt(16)
; DI unsigned pk2(float a, float b) { f32x2 v = {a, b}; bf16v2 r = __builtin_convertvector(v, bf16v2); return __builtin_bit_cast(unsigned, r); }
; DI float bf_lo(unsigned u) { return __uint_as_float(u << 16); }
; DI float bf_hi(unsigned u) { return __uint_as_float(u & 0xffff0000u); }
; DI float silu_mul(float o, float g) { return o * g * __builtin_amdgcn_rcpf(1.0f + __builtin_amdgcn_exp2f(g * -1.4426950408889634f)); }
; DI void attnA_item(bf16_t* z, const float* sinks, int hp, int qs, LAS bf16_t* vs, const LAS float* btab, int lane) {
;     ...
;                 for (int g = 0; g < 4; ++g) {
;                     const int d0 = (dt << 9) | (g << 7);
;                     const u32x2 gv = *(const u32x2*)(grow + d0);
;                     u32x2 o; o.x = pk2(silu_mul(acc[u][dt][4 * g] * inv, bf_lo(gv.x)), silu_mul(acc[u][dt][4 * g + 1] * inv, bf_hi(gv.x)));
;                     o.y = pk2(silu_mul(acc[u][dt][4 * g + 2] * inv, bf_lo(gv.y)), silu_mul(acc[u][dt][4 * g + 3] * inv, bf_hi(gv.y)));
	v_lshlrev_b32_e32 v210, 16, v178
	v_and_b32_e32 v211, 0xffff0000, v178
	v_lshlrev_b32_e32 v212, 16, v179
	v_and_b32_e32 v213, 0xffff0000, v179
	v_mul_f32_e32 v214, 0xbfb8aa3b, v210
	v_mul_f32_e32 v215, 0xbfb8aa3b, v211
	v_mul_f32_e32 v216, 0xbfb8aa3b, v212
	v_mul_f32_e32 v217, 0xbfb8aa3b, v213
	v_exp_f32_e32 v214, v214
	v_exp_f32_e32 v215, v215
	v_exp_f32_e32 v216, v216
	v_exp_f32_e32 v217, v217
	v_pk_mul_f32 v[50:51], v[50:51], v[210:211]
	v_pk_mul_f32 v[52:53], v[52:53], v[212:213]
	v_add_f32_e32 v214, 1.0, v214
	v_add_f32_e32 v215, 1.0, v215
	v_add_f32_e32 v216, 1.0, v216
	v_add_f32_e32 v217, 1.0, v217
	v_rcp_f32_e32 v214, v214
	v_rcp_f32_e32 v215, v215
	v_rcp_f32_e32 v216, v216
	v_rcp_f32_e32 v217, v217
	v_pk_mul_f32 v[50:51], v[50:51], v[214:215]
	v_pk_mul_f32 v[52:53], v[52:53], v[216:217]
	v_cvt_pk_bf16_f32 v50, v50, v51
	v_cvt_pk_bf16_f32 v51, v52, v53
	s_waitcnt vmcnt(15)
	v_lshlrev_b32_e32 v218, 16, v180
	v_and_b32_e32 v219, 0xffff0000, v180
	v_lshlrev_b32_e32 v220, 16, v181
	v_and_b32_e32 v221, 0xffff0000, v181
	v_mul_f32_e32 v222, 0xbfb8aa3b, v218
	v_mul_f32_e32 v223, 0xbfb8aa3b, v219
	v_mul_f32_e32 v224, 0xbfb8aa3b, v220
	v_mul_f32_e32 v225, 0xbfb8aa3b, v221
	v_exp_f32_e32 v222, v222
	v_exp_f32_e32 v223, v223
	v_exp_f32_e32 v224, v224
	v_exp_f32_e32 v225, v225
	v_pk_mul_f32 v[54:55], v[54:55], v[218:219]
	v_pk_mul_f32 v[56:57], v[56:57], v[220:221]
	v_add_f32_e32 v222, 1.0, v222
	v_add_f32_e32 v223, 1.0, v223
	v_add_f32_e32 v224, 1.0, v224
	v_add_f32_e32 v225, 1.0, v225
	v_rcp_f32_e32 v222, v222
	v_rcp_f32_e32 v223, v223
	v_rcp_f32_e32 v224, v224
	v_rcp_f32_e32 v225, v225
	v_pk_mul_f32 v[54:55], v[54:55], v[222:223]
	v_pk_mul_f32 v[56:57], v[56:57], v[224:225]
	v_cvt_pk_bf16_f32 v54, v54, v55
	v_cvt_pk_bf16_f32 v55, v56, v57
	s_waitcnt vmcnt(14)
	v_lshlrev_b32_e32 v210, 16, v182
	v_and_b32_e32 v211, 0xffff0000, v182
	v_lshlrev_b32_e32 v212, 16, v183
	v_and_b32_e32 v213, 0xffff0000, v183
	v_mul_f32_e32 v214, 0xbfb8aa3b, v210
	v_mul_f32_e32 v215, 0xbfb8aa3b, v211
	v_mul_f32_e32 v216, 0xbfb8aa3b, v212
	v_mul_f32_e32 v217, 0xbfb8aa3b, v213
	v_exp_f32_e32 v214, v214
	v_exp_f32_e32 v215, v215
	v_exp_f32_e32 v216, v216
	v_exp_f32_e32 v217, v217
	v_pk_mul_f32 v[58:59], v[58:59], v[210:211]
	v_pk_mul_f32 v[60:61], v[60:61], v[212:213]
	v_add_f32_e32 v214, 1.0, v214
	v_add_f32_e32 v215, 1.0, v215
	v_add_f32_e32 v216, 1.0, v216
	v_add_f32_e32 v217, 1.0, v217
	v_rcp_f32_e32 v214, v214
	v_rcp_f32_e32 v215, v215
	v_rcp_f32_e32 v216, v216
	v_rcp_f32_e32 v217, v217
	v_pk_mul_f32 v[58:59], v[58:59], v[214:215]
	v_pk_mul_f32 v[60:61], v[60:61], v[216:217]
	v_cvt_pk_bf16_f32 v58, v58, v59
	v_cvt_pk_bf16_f32 v59, v60, v61
	s_waitcnt vmcnt(13)
	v_lshlrev_b32_e32 v218, 16, v184
	v_and_b32_e32 v219, 0xffff0000, v184
	v_lshlrev_b32_e32 v220, 16, v185
	v_and_b32_e32 v221, 0xffff0000, v185
	v_mul_f32_e32 v222, 0xbfb8aa3b, v218
	v_mul_f32_e32 v223, 0xbfb8aa3b, v219
	v_mul_f32_e32 v224, 0xbfb8aa3b, v220
	v_mul_f32_e32 v225, 0xbfb8aa3b, v221
	v_exp_f32_e32 v222, v222
	v_exp_f32_e32 v223, v223
	v_exp_f32_e32 v224, v224
	v_exp_f32_e32 v225, v225
	v_pk_mul_f32 v[62:63], v[62:63], v[218:219]
	v_pk_mul_f32 v[64:65], v[64:65], v[220:221]
	v_add_f32_e32 v222, 1.0, v222
	v_add_f32_e32 v223, 1.0, v223
	v_add_f32_e32 v224, 1.0, v224
	v_add_f32_e32 v225, 1.0, v225
	v_rcp_f32_e32 v222, v222
	v_rcp_f32_e32 v223, v223
	v_rcp_f32_e32 v224, v224
	v_rcp_f32_e32 v225, v225
	v_pk_mul_f32 v[62:63], v[62:63], v[222:223]
	v_pk_mul_f32 v[64:65], v[64:65], v[224:225]
	v_cvt_pk_bf16_f32 v62, v62, v63
	v_cvt_pk_bf16_f32 v63, v64, v65
	s_waitcnt vmcnt(12)
	v_lshlrev_b32_e32 v210, 16, v186
	v_and_b32_e32 v211, 0xffff0000, v186
	v_lshlrev_b32_e32 v212, 16, v187
	v_and_b32_e32 v213, 0xffff0000, v187
	v_mul_f32_e32 v214, 0xbfb8aa3b, v210
	v_mul_f32_e32 v215, 0xbfb8aa3b, v211
	v_mul_f32_e32 v216, 0xbfb8aa3b, v212
	v_mul_f32_e32 v217, 0xbfb8aa3b, v213
	v_exp_f32_e32 v214, v214
	v_exp_f32_e32 v215, v215
	v_exp_f32_e32 v216, v216
	v_exp_f32_e32 v217, v217
	v_pk_mul_f32 v[34:35], v[34:35], v[210:211]
	v_pk_mul_f32 v[36:37], v[36:37], v[212:213]
	v_add_f32_e32 v214, 1.0, v214
	v_add_f32_e32 v215, 1.0, v215
	v_add_f32_e32 v216, 1.0, v216
	v_add_f32_e32 v217, 1.0, v217
	v_rcp_f32_e32 v214, v214
	v_rcp_f32_e32 v215, v215
	v_rcp_f32_e32 v216, v216
	v_rcp_f32_e32 v217, v217
	v_pk_mul_f32 v[34:35], v[34:35], v[214:215]
	v_pk_mul_f32 v[36:37], v[36:37], v[216:217]
	v_cvt_pk_bf16_f32 v34, v34, v35
	v_cvt_pk_bf16_f32 v35, v36, v37
	s_waitcnt vmcnt(11)
	v_lshlrev_b32_e32 v218, 16, v188
	v_and_b32_e32 v219, 0xffff0000, v188
	v_lshlrev_b32_e32 v220, 16, v189
	v_and_b32_e32 v221, 0xffff0000, v189
	v_mul_f32_e32 v222, 0xbfb8aa3b, v218
	v_mul_f32_e32 v223, 0xbfb8aa3b, v219
	v_mul_f32_e32 v224, 0xbfb8aa3b, v220
	v_mul_f32_e32 v225, 0xbfb8aa3b, v221
	v_exp_f32_e32 v222, v222
	v_exp_f32_e32 v223, v223
	v_exp_f32_e32 v224, v224
	v_exp_f32_e32 v225, v225
	v_pk_mul_f32 v[38:39], v[38:39], v[218:219]
	v_pk_mul_f32 v[40:41], v[40:41], v[220:221]
	v_add_f32_e32 v222, 1.0, v222
	v_add_f32_e32 v223, 1.0, v223
	v_add_f32_e32 v224, 1.0, v224
	v_add_f32_e32 v225, 1.0, v225
	v_rcp_f32_e32 v222, v222
	v_rcp_f32_e32 v223, v223
	v_rcp_f32_e32 v224, v224
	v_rcp_f32_e32 v225, v225
	v_pk_mul_f32 v[38:39], v[38:39], v[222:223]
	v_pk_mul_f32 v[40:41], v[40:41], v[224:225]
	v_cvt_pk_bf16_f32 v38, v38, v39
	v_cvt_pk_bf16_f32 v39, v40, v41
	s_waitcnt vmcnt(10)
; DI unsigned pk2(float a, float b) { f32x2 v = {a, b}; bf16v2 r = __builtin_convertvector(v, bf16v2); return __builtin_bit_cast(unsigned, r); }
; DI float bf_lo(unsigned u) { return __uint_as_float(u << 16); }
; DI float bf_hi(unsigned u) { return __uint_as_float(u & 0xffff0000u); }
; DI float silu_mul(float o, float g) { return o * g * __builtin_amdgcn_rcpf(1.0f + __builtin_amdgcn_exp2f(g * -1.4426950408889634f)); }
; DI void attnA_item(bf16_t* z, const float* sinks, int hp, int qs, LAS bf16_t* vs, const LAS float* btab, int lane) {
;     ...
;                 for (int g = 0; g < 4; ++g) {
;                     const int d0 = (dt << 9) | (g << 7);
;                     const u32x2 gv = *(const u32x2*)(grow + d0);
;                     u32x2 o; o.x = pk2(silu_mul(acc[u][dt][4 * g] * inv, bf_lo(gv.x)), silu_mul(acc[u][dt][4 * g + 1] * inv, bf_hi(gv.x)));
;                     o.y = pk2(silu_mul(acc[u][dt][4 * g + 2] * inv, bf_lo(gv.y)), silu_mul(acc[u][dt][4 * g + 3] * inv, bf_hi(gv.y)));
	v_lshlrev_b32_e32 v210, 16, v190
	v_and_b32_e32 v211, 0xffff0000, v190
	v_lshlrev_b32_e32 v212, 16, v191
	v_and_b32_e32 v213, 0xffff0000, v191
	v_mul_f32_e32 v214, 0xbfb8aa3b, v210
	v_mul_f32_e32 v215, 0xbfb8aa3b, v211
	v_mul_f32_e32 v216, 0xbfb8aa3b, v212
	v_mul_f32_e32 v217, 0xbfb8aa3b, v213
	v_exp_f32_e32 v214, v214
	v_exp_f32_e32 v215, v215
	v_exp_f32_e32 v216, v216
	v_exp_f32_e32 v217, v217
	v_pk_mul_f32 v[42:43], v[42:43], v[210:211]
	v_pk_mul_f32 v[44:45], v[44:45], v[212:213]
	v_add_f32_e32 v214, 1.0, v214
	v_add_f32_e32 v215, 1.0, v215
	v_add_f32_e32 v216, 1.0, v216
	v_add_f32_e32 v217, 1.0, v217
	v_rcp_f32_e32 v214, v214
	v_rcp_f32_e32 v215, v215
	v_rcp_f32_e32 v216, v216
	v_rcp_f32_e32 v217, v217
	v_pk_mul_f32 v[42:43], v[42:43], v[214:215]
	v_pk_mul_f32 v[44:45], v[44:45], v[216:217]
	v_cvt_pk_bf16_f32 v42, v42, v43
	v_cvt_pk_bf16_f32 v43, v44, v45
	s_waitcnt vmcnt(9)
	v_lshlrev_b32_e32 v218, 16, v192
	v_and_b32_e32 v219, 0xffff0000, v192
	v_lshlrev_b32_e32 v220, 16, v193
	v_and_b32_e32 v221, 0xffff0000, v193
	v_mul_f32_e32 v222, 0xbfb8aa3b, v218
	v_mul_f32_e32 v223, 0xbfb8aa3b, v219
	v_mul_f32_e32 v224, 0xbfb8aa3b, v220
	v_mul_f32_e32 v225, 0xbfb8aa3b, v221
	v_exp_f32_e32 v222, v222
	v_exp_f32_e32 v223, v223
	v_exp_f32_e32 v224, v224
	v_exp_f32_e32 v225, v225
	v_pk_mul_f32 v[46:47], v[46:47], v[218:219]
	v_pk_mul_f32 v[48:49], v[48:49], v[220:221]
	v_add_f32_e32 v222, 1.0, v222
	v_add_f32_e32 v223, 1.0, v223
	v_add_f32_e32 v224, 1.0, v224
	v_add_f32_e32 v225, 1.0, v225
	v_rcp_f32_e32 v222, v222
	v_rcp_f32_e32 v223, v223
	v_rcp_f32_e32 v224, v224
	v_rcp_f32_e32 v225, v225
	v_pk_mul_f32 v[46:47], v[46:47], v[222:223]
	v_pk_mul_f32 v[48:49], v[48:49], v[224:225]
	v_cvt_pk_bf16_f32 v46, v46, v47
	v_cvt_pk_bf16_f32 v47, v48, v49
	s_waitcnt vmcnt(8)
	v_lshlrev_b32_e32 v210, 16, v194
	v_and_b32_e32 v211, 0xffff0000, v194
	v_lshlrev_b32_e32 v212, 16, v195
	v_and_b32_e32 v213, 0xffff0000, v195
	v_mul_f32_e32 v214, 0xbfb8aa3b, v210
	v_mul_f32_e32 v215, 0xbfb8aa3b, v211
	v_mul_f32_e32 v216, 0xbfb8aa3b, v212
	v_mul_f32_e32 v217, 0xbfb8aa3b, v213
	v_exp_f32_e32 v214, v214
	v_exp_f32_e32 v215, v215
	v_exp_f32_e32 v216, v216
	v_exp_f32_e32 v217, v217
	v_pk_mul_f32 v[18:19], v[18:19], v[210:211]
	v_pk_mul_f32 v[20:21], v[20:21], v[212:213]
	v_add_f32_e32 v214, 1.0, v214
	v_add_f32_e32 v215, 1.0, v215
	v_add_f32_e32 v216, 1.0, v216
	v_add_f32_e32 v217, 1.0, v217
	v_rcp_f32_e32 v214, v214
	v_rcp_f32_e32 v215, v215
	v_rcp_f32_e32 v216, v216
	v_rcp_f32_e32 v217, v217
	v_pk_mul_f32 v[18:19], v[18:19], v[214:215]
	v_pk_mul_f32 v[20:21], v[20:21], v[216:217]
	v_cvt_pk_bf16_f32 v18, v18, v19
	v_cvt_pk_bf16_f32 v19, v20, v21
	s_waitcnt vmcnt(7)
	v_lshlrev_b32_e32 v218, 16, v196
	v_and_b32_e32 v219, 0xffff0000, v196
	v_lshlrev_b32_e32 v220, 16, v197
	v_and_b32_e32 v221, 0xffff0000, v197
	v_mul_f32_e32 v222, 0xbfb8aa3b, v218
	v_mul_f32_e32 v223, 0xbfb8aa3b, v219
	v_mul_f32_e32 v224, 0xbfb8aa3b, v220
	v_mul_f32_e32 v225, 0xbfb8aa3b, v221
	v_exp_f32_e32 v222, v222
	v_exp_f32_e32 v223, v223
	v_exp_f32_e32 v224, v224
	v_exp_f32_e32 v225, v225
	v_pk_mul_f32 v[22:23], v[22:23], v[218:219]
	v_pk_mul_f32 v[24:25], v[24:25], v[220:221]
	v_add_f32_e32 v222, 1.0, v222
	v_add_f32_e32 v223, 1.0, v223
	v_add_f32_e32 v224, 1.0, v224
	v_add_f32_e32 v225, 1.0, v225
	v_rcp_f32_e32 v222, v222
	v_rcp_f32_e32 v223, v223
	v_rcp_f32_e32 v224, v224
	v_rcp_f32_e32 v225, v225
	v_pk_mul_f32 v[22:23], v[22:23], v[222:223]
	v_pk_mul_f32 v[24:25], v[24:25], v[224:225]
	v_cvt_pk_bf16_f32 v22, v22, v23
	v_cvt_pk_bf16_f32 v23, v24, v25
	s_waitcnt vmcnt(6)
	v_lshlrev_b32_e32 v210, 16, v198
	v_and_b32_e32 v211, 0xffff0000, v198
	v_lshlrev_b32_e32 v212, 16, v199
	v_and_b32_e32 v213, 0xffff0000, v199
	v_mul_f32_e32 v214, 0xbfb8aa3b, v210
	v_mul_f32_e32 v215, 0xbfb8aa3b, v211
	v_mul_f32_e32 v216, 0xbfb8aa3b, v212
	v_mul_f32_e32 v217, 0xbfb8aa3b, v213
	v_exp_f32_e32 v214, v214
	v_exp_f32_e32 v215, v215
	v_exp_f32_e32 v216, v216
	v_exp_f32_e32 v217, v217
	v_pk_mul_f32 v[26:27], v[26:27], v[210:211]
	v_pk_mul_f32 v[28:29], v[28:29], v[212:213]
	v_add_f32_e32 v214, 1.0, v214
	v_add_f32_e32 v215, 1.0, v215
	v_add_f32_e32 v216, 1.0, v216
	v_add_f32_e32 v217, 1.0, v217
	v_rcp_f32_e32 v214, v214
	v_rcp_f32_e32 v215, v215
	v_rcp_f32_e32 v216, v216
	v_rcp_f32_e32 v217, v217
	v_pk_mul_f32 v[26:27], v[26:27], v[214:215]
	v_pk_mul_f32 v[28:29], v[28:29], v[216:217]
	v_cvt_pk_bf16_f32 v26, v26, v27
	v_cvt_pk_bf16_f32 v27, v28, v29
	s_waitcnt vmcnt(5)
	v_lshlrev_b32_e32 v218, 16, v200
	v_and_b32_e32 v219, 0xffff0000, v200
	v_lshlrev_b32_e32 v220, 16, v201
	v_and_b32_e32 v221, 0xffff0000, v201
	v_mul_f32_e32 v222, 0xbfb8aa3b, v218
	v_mul_f32_e32 v223, 0xbfb8aa3b, v219
	v_mul_f32_e32 v224, 0xbfb8aa3b, v220
	v_mul_f32_e32 v225, 0xbfb8aa3b, v221
	v_exp_f32_e32 v222, v222
	v_exp_f32_e32 v223, v223
	v_exp_f32_e32 v224, v224
	v_exp_f32_e32 v225, v225
	v_pk_mul_f32 v[30:31], v[30:31], v[218:219]
	v_pk_mul_f32 v[32:33], v[32:33], v[220:221]
	v_add_f32_e32 v222, 1.0, v222
	v_add_f32_e32 v223, 1.0, v223
	v_add_f32_e32 v224, 1.0, v224
	v_add_f32_e32 v225, 1.0, v225
	v_rcp_f32_e32 v222, v222
	v_rcp_f32_e32 v223, v223
	v_rcp_f32_e32 v224, v224
	v_rcp_f32_e32 v225, v225
	v_pk_mul_f32 v[30:31], v[30:31], v[222:223]
	v_pk_mul_f32 v[32:33], v[32:33], v[224:225]
	v_cvt_pk_bf16_f32 v30, v30, v31
	v_cvt_pk_bf16_f32 v31, v32, v33
	s_waitcnt vmcnt(4)
; DI unsigned pk2(float a, float b) { f32x2 v = {a, b}; bf16v2 r = __builtin_convertvector(v, bf16v2); return __builtin_bit_cast(unsigned, r); }
; DI float bf_lo(unsigned u) { return __uint_as_float(u << 16); }
; DI float bf_hi(unsigned u) { return __uint_as_float(u & 0xffff0000u); }
; DI float silu_mul(float o, float g) { return o * g * __builtin_amdgcn_rcpf(1.0f + __builtin_amdgcn_exp2f(g * -1.4426950408889634f)); }
; DI void attnA_item(bf16_t* z, const float* sinks, int hp, int qs, LAS bf16_t* vs, const LAS float* btab, int lane) {
;     ...
;                 for (int g = 0; g < 4; ++g) {
;                     const int d0 = (dt << 9) | (g << 7);
;                     const u32x2 gv = *(const u32x2*)(grow + d0);
;                     u32x2 o; o.x = pk2(silu_mul(acc[u][dt][4 * g] * inv, bf_lo(gv.x)), silu_mul(acc[u][dt][4 * g + 1] * inv, bf_hi(gv.x)));
;                     o.y = pk2(silu_mul(acc[u][dt][4 * g + 2] * inv, bf_lo(gv.y)), silu_mul(acc[u][dt][4 * g + 3] * inv, bf_hi(gv.y)));
;                     *(u32x2*)(orow + d0) = o;
	v_lshlrev_b32_e32 v210, 16, v202
	v_and_b32_e32 v211, 0xffff0000, v202
	v_lshlrev_b32_e32 v212, 16, v203
	v_and_b32_e32 v213, 0xffff0000, v203
	v_mul_f32_e32 v214, 0xbfb8aa3b, v210
	v_mul_f32_e32 v215, 0xbfb8aa3b, v211
	v_mul_f32_e32 v216, 0xbfb8aa3b, v212
	v_mul_f32_e32 v217, 0xbfb8aa3b, v213
	v_exp_f32_e32 v214, v214
	v_exp_f32_e32 v215, v215
	v_exp_f32_e32 v216, v216
	v_exp_f32_e32 v217, v217
	v_pk_mul_f32 v[2:3], v[2:3], v[210:211]
	v_pk_mul_f32 v[4:5], v[4:5], v[212:213]
	v_add_f32_e32 v214, 1.0, v214
	v_add_f32_e32 v215, 1.0, v215
	v_add_f32_e32 v216, 1.0, v216
	v_add_f32_e32 v217, 1.0, v217
	v_rcp_f32_e32 v214, v214
	v_rcp_f32_e32 v215, v215
	v_rcp_f32_e32 v216, v216
	v_rcp_f32_e32 v217, v217
	v_pk_mul_f32 v[2:3], v[2:3], v[214:215]
	v_pk_mul_f32 v[4:5], v[4:5], v[216:217]
	v_cvt_pk_bf16_f32 v2, v2, v3
	v_cvt_pk_bf16_f32 v3, v4, v5
	s_waitcnt vmcnt(3)
	v_lshlrev_b32_e32 v218, 16, v204
	v_and_b32_e32 v219, 0xffff0000, v204
	v_lshlrev_b32_e32 v220, 16, v205
	v_and_b32_e32 v221, 0xffff0000, v205
	v_mul_f32_e32 v222, 0xbfb8aa3b, v218
	v_mul_f32_e32 v223, 0xbfb8aa3b, v219
	v_mul_f32_e32 v224, 0xbfb8aa3b, v220
	v_mul_f32_e32 v225, 0xbfb8aa3b, v221
	v_exp_f32_e32 v222, v222
	v_exp_f32_e32 v223, v223
	v_exp_f32_e32 v224, v224
	v_exp_f32_e32 v225, v225
	v_pk_mul_f32 v[6:7], v[6:7], v[218:219]
	v_pk_mul_f32 v[8:9], v[8:9], v[220:221]
	v_add_f32_e32 v222, 1.0, v222
	v_add_f32_e32 v223, 1.0, v223
	v_add_f32_e32 v224, 1.0, v224
	v_add_f32_e32 v225, 1.0, v225
	v_rcp_f32_e32 v222, v222
	v_rcp_f32_e32 v223, v223
	v_rcp_f32_e32 v224, v224
	v_rcp_f32_e32 v225, v225
	v_pk_mul_f32 v[6:7], v[6:7], v[222:223]
	v_pk_mul_f32 v[8:9], v[8:9], v[224:225]
	v_cvt_pk_bf16_f32 v6, v6, v7
	v_cvt_pk_bf16_f32 v7, v8, v9
	s_waitcnt vmcnt(2)
	v_lshlrev_b32_e32 v210, 16, v206
	v_and_b32_e32 v211, 0xffff0000, v206
	v_lshlrev_b32_e32 v212, 16, v207
	v_and_b32_e32 v213, 0xffff0000, v207
	v_mul_f32_e32 v214, 0xbfb8aa3b, v210
	v_mul_f32_e32 v215, 0xbfb8aa3b, v211
	v_mul_f32_e32 v216, 0xbfb8aa3b, v212
	v_mul_f32_e32 v217, 0xbfb8aa3b, v213
	v_exp_f32_e32 v214, v214
	v_exp_f32_e32 v215, v215
	v_exp_f32_e32 v216, v216
	v_exp_f32_e32 v217, v217
	v_pk_mul_f32 v[10:11], v[10:11], v[210:211]
	v_pk_mul_f32 v[12:13], v[12:13], v[212:213]
	v_add_f32_e32 v214, 1.0, v214
	v_add_f32_e32 v215, 1.0, v215
	v_add_f32_e32 v216, 1.0, v216
	v_add_f32_e32 v217, 1.0, v217
	v_rcp_f32_e32 v214, v214
	v_rcp_f32_e32 v215, v215
	v_rcp_f32_e32 v216, v216
	v_rcp_f32_e32 v217, v217
	v_pk_mul_f32 v[10:11], v[10:11], v[214:215]
	v_pk_mul_f32 v[12:13], v[12:13], v[216:217]
	v_cvt_pk_bf16_f32 v10, v10, v11
	v_cvt_pk_bf16_f32 v11, v12, v13
	s_waitcnt vmcnt(1)
	v_lshlrev_b32_e32 v218, 16, v208
	v_and_b32_e32 v219, 0xffff0000, v208
	v_lshlrev_b32_e32 v220, 16, v209
	v_and_b32_e32 v221, 0xffff0000, v209
	v_mul_f32_e32 v222, 0xbfb8aa3b, v218
	v_mul_f32_e32 v223, 0xbfb8aa3b, v219
	v_mul_f32_e32 v224, 0xbfb8aa3b, v220
	v_mul_f32_e32 v225, 0xbfb8aa3b, v221
	v_exp_f32_e32 v222, v222
	v_exp_f32_e32 v223, v223
	v_exp_f32_e32 v224, v224
	v_exp_f32_e32 v225, v225
	v_pk_mul_f32 v[14:15], v[14:15], v[218:219]
	v_pk_mul_f32 v[16:17], v[16:17], v[220:221]
	v_add_f32_e32 v222, 1.0, v222
	v_add_f32_e32 v223, 1.0, v223
	v_add_f32_e32 v224, 1.0, v224
	v_add_f32_e32 v225, 1.0, v225
	v_rcp_f32_e32 v222, v222
	v_rcp_f32_e32 v223, v223
	v_rcp_f32_e32 v224, v224
	v_rcp_f32_e32 v225, v225
	v_pk_mul_f32 v[14:15], v[14:15], v[222:223]
	v_pk_mul_f32 v[16:17], v[16:17], v[224:225]
	v_cvt_pk_bf16_f32 v14, v14, v15
	v_cvt_pk_bf16_f32 v15, v16, v17
	global_store_dwordx2 v[138:139], v[50:51], off nt
	global_store_dwordx2 v[138:139], v[54:55], off offset:256 nt
	global_store_dwordx2 v[138:139], v[58:59], off offset:512 nt
	global_store_dwordx2 v[138:139], v[62:63], off offset:768 nt
	global_store_dwordx2 v[138:139], v[34:35], off offset:1024 nt
	global_store_dwordx2 v[138:139], v[38:39], off offset:1280 nt
	global_store_dwordx2 v[138:139], v[42:43], off offset:1536 nt
	global_store_dwordx2 v[138:139], v[46:47], off offset:1792 nt
	global_store_dwordx2 v[142:143], v[18:19], off nt
	global_store_dwordx2 v[142:143], v[22:23], off offset:256 nt
	global_store_dwordx2 v[142:143], v[26:27], off offset:512 nt
	global_store_dwordx2 v[142:143], v[30:31], off offset:768 nt
	global_store_dwordx2 v[142:143], v[2:3], off offset:1024 nt
	global_store_dwordx2 v[142:143], v[6:7], off offset:1280 nt
	global_store_dwordx2 v[142:143], v[10:11], off offset:1536 nt
	global_store_dwordx2 v[142:143], v[14:15], off offset:1792 nt
	s_branch .LBB0_177
